# mla_row phase: rope element and rope-table loads issued with the row's q/kv loads (one memory round trip per row instead of three)
# speedup vs baseline: 1.0049x; 1.0049x over previous
.LBB0_376:
	s_or_b64 exec, exec, s[2:3]
	v_lshl_add_u64 v[12:13], s[14:15], 0, v[30:31]
	global_load_dwordx4 v[12:15], v[12:13], off
	v_lshl_add_u64 v[50:51], s[14:15], 0, v[34:35]
	global_load_dword v49, v[50:51], off
	s_lshr_b32 s0, s12, 6
	v_mov_b32_e32 v52, s12
	v_mov_b32_e32 v53, s0
	v_cndmask_b32_e64 v52, v52, v53, s[8:9]
	v_lshlrev_b32_e32 v52, 4, v52
	s_movk_i32 s0, 0x3f0
	v_and_or_b32 v52, v52, s0, v42
	v_lshlrev_b32_e32 v52, 3, v52
	global_load_dwordx2 v[54:55], v52, s[16:17]
	s_waitcnt vmcnt(0)
	v_mul_f32_e32 v43, v21, v21
	v_mul_f32_e32 v44, v23, v23
	v_fmac_f32_e32 v43, v20, v20
	v_fmac_f32_e32 v44, v22, v22
	v_add_f32_e32 v43, v43, v44
	v_mul_f32_e32 v44, v17, v17
	v_mul_f32_e32 v45, v19, v19
	v_fmac_f32_e32 v44, v16, v16
	v_fmac_f32_e32 v45, v18, v18
	v_add_f32_e32 v44, v44, v45
	v_add_f32_e32 v43, v44, v43
	ds_bpermute_b32 v44, v36, v43
	s_waitcnt lgkmcnt(0)
	v_add_f32_e32 v43, v43, v44
	ds_bpermute_b32 v44, v37, v43
	s_waitcnt lgkmcnt(0)
	v_add_f32_e32 v43, v43, v44
	ds_bpermute_b32 v44, v38, v43
	s_waitcnt lgkmcnt(0)
	v_add_f32_e32 v43, v43, v44
	ds_bpermute_b32 v44, v39, v43
	s_waitcnt lgkmcnt(0)
	v_add_f32_e32 v43, v43, v44
	ds_bpermute_b32 v44, v40, v43
	s_waitcnt lgkmcnt(0)
	v_add_f32_e32 v43, v43, v44
	ds_bpermute_b32 v44, v41, v43
	s_and_saveexec_b64 s[36:37], s[6:7]
	s_cbranch_execz .LBB0_378
	s_waitcnt lgkmcnt(0)
	v_add_f32_e32 v43, v43, v44
	v_fmamk_f32 v43, v43, 0x3b2aaaab, v193
	v_mul_f32_e32 v44, 0x4f800000, v43
	v_cmp_gt_f32_e32 vcc, s67, v43
	s_nop 1
	v_cndmask_b32_e32 v43, v43, v44, vcc
	v_sqrt_f32_e32 v44, v43
	s_nop 0
	v_add_u32_e32 v45, -1, v44
	v_fma_f32 v47, -v45, v44, v43
	v_add_u32_e32 v46, 1, v44
	v_cmp_ge_f32_e64 s[2:3], 0, v47
	s_nop 1
	v_cndmask_b32_e64 v45, v44, v45, s[2:3]
	v_fma_f32 v44, -v46, v44, v43
	v_cmp_lt_f32_e64 s[2:3], 0, v44
	s_nop 1
	v_cndmask_b32_e64 v44, v45, v46, s[2:3]
	v_mul_f32_e32 v45, 0x37800000, v44
	v_cndmask_b32_e32 v44, v44, v45, vcc
	v_cmp_class_f32_e32 vcc, v43, v195
	s_nop 1
	v_cndmask_b32_e32 v43, v44, v43, vcc
	v_div_scale_f32 v44, s[0:1], v43, v43, 1.0
	v_rcp_f32_e32 v45, v44
	s_nop 0
	v_fma_f32 v46, -v44, v45, 1.0
	v_fmac_f32_e32 v45, v46, v45
	v_div_scale_f32 v46, vcc, 1.0, v43, 1.0
	v_mul_f32_e32 v47, v46, v45
	v_fma_f32 v48, -v44, v47, v46
	v_fmac_f32_e32 v47, v48, v45
	v_fma_f32 v44, -v44, v47, v46
	v_div_fmas_f32 v44, v44, v45, v47
	v_div_fixup_f32 v44, v44, v43, 1.0
	v_pk_mul_f32 v[20:21], v[20:21], v[44:45] op_sel_hi:[1,0]
	v_pk_mul_f32 v[22:23], v[22:23], v[44:45] op_sel_hi:[1,0]
	v_pk_mul_f32 v[16:17], v[16:17], v[44:45] op_sel_hi:[1,0]
	v_pk_mul_f32 v[20:21], v[4:5], v[20:21]
	v_pk_mul_f32 v[22:23], v[6:7], v[22:23]
	v_pk_mul_f32 v[16:17], v[0:1], v[16:17]
	v_cvt_pk_bf16_f32 v20, v20, v21
	v_cvt_pk_bf16_f32 v21, v22, v23
	v_cvt_pk_bf16_f32 v22, v16, v17
	v_pk_mul_f32 v[16:17], v[18:19], v[44:45] op_sel_hi:[1,0]
	s_nop 0
	v_pk_mul_f32 v[16:17], v[2:3], v[16:17]
	s_nop 0
	v_cvt_pk_bf16_f32 v23, v16, v17
	v_lshl_add_u64 v[16:17], s[14:15], 0, v[24:25]
	global_store_dwordx4 v[16:17], v[20:23], off
.LBB0_378:
	s_or_b64 exec, exec, s[36:37]
	v_pk_mul_f32 v[16:17], v[14:15], v[14:15]
	v_pk_mul_f32 v[18:19], v[12:13], v[12:13]
	s_cmpk_gt_i32 s12, 0x7fff
	v_pk_mov_b32 v[20:21], v[18:19], v[16:17] op_sel:[1,0]
	v_mov_b32_e32 v19, v17
	v_pk_add_f32 v[16:17], v[20:21], v[18:19]
	s_nop 0
	v_add_f32_e32 v16, v16, v17
	ds_bpermute_b32 v17, v36, v16
	s_waitcnt lgkmcnt(0)
	v_add_f32_e32 v16, v16, v17
	ds_bpermute_b32 v17, v37, v16
	s_waitcnt lgkmcnt(0)
	v_add_f32_e32 v16, v16, v17
	ds_bpermute_b32 v17, v38, v16
	s_waitcnt lgkmcnt(0)
	v_add_f32_e32 v16, v16, v17
	ds_bpermute_b32 v17, v39, v16
	s_waitcnt lgkmcnt(0)
	v_add_f32_e32 v16, v16, v17
	ds_bpermute_b32 v17, v40, v16
	s_waitcnt lgkmcnt(0)
	v_add_f32_e32 v16, v16, v17
	ds_bpermute_b32 v17, v41, v16
	s_waitcnt lgkmcnt(0)
	v_add_f32_e32 v16, v16, v17
	v_fmamk_f32 v16, v16, 0x3b800000, v193
	v_cmp_gt_f32_e32 vcc, s67, v16
	v_mul_f32_e32 v17, 0x4f800000, v16
	s_nop 0
	v_cndmask_b32_e32 v16, v16, v17, vcc
	v_sqrt_f32_e32 v17, v16
	s_nop 0
	v_add_u32_e32 v18, -1, v17
	v_fma_f32 v19, -v18, v17, v16
	v_cmp_ge_f32_e64 s[2:3], 0, v19
	v_add_u32_e32 v19, 1, v17
	s_nop 0
	v_cndmask_b32_e64 v18, v17, v18, s[2:3]
	v_fma_f32 v17, -v19, v17, v16
	v_cmp_lt_f32_e64 s[2:3], 0, v17
	s_nop 1
	v_cndmask_b32_e64 v17, v18, v19, s[2:3]
	v_mul_f32_e32 v18, 0x37800000, v17
	v_cndmask_b32_e32 v17, v17, v18, vcc
	v_cmp_class_f32_e32 vcc, v16, v195
	s_nop 1
	v_cndmask_b32_e32 v16, v17, v16, vcc
	v_div_scale_f32 v17, s[0:1], v16, v16, 1.0
	v_rcp_f32_e32 v18, v17
	s_nop 0
	v_fma_f32 v19, -v17, v18, 1.0
	v_fmac_f32_e32 v18, v19, v18
	v_div_scale_f32 v19, vcc, 1.0, v16, 1.0
	v_mul_f32_e32 v20, v19, v18
	v_fma_f32 v21, -v17, v20, v19
	v_fmac_f32_e32 v20, v21, v18
	v_fma_f32 v17, -v17, v20, v19
	v_div_fmas_f32 v17, v17, v18, v20
	v_div_fixup_f32 v16, v17, v16, 1.0
	v_pk_mul_f32 v[12:13], v[12:13], v[16:17] op_sel_hi:[1,0]
	v_pk_mul_f32 v[14:15], v[14:15], v[16:17] op_sel_hi:[1,0]
	v_pk_mul_f32 v[12:13], v[8:9], v[12:13]
	v_pk_mul_f32 v[14:15], v[10:11], v[14:15]
	v_cvt_pk_bf16_f32 v12, v12, v13
	v_cvt_pk_bf16_f32 v13, v14, v15
	v_lshl_add_u64 v[14:15], s[14:15], 0, v[28:29]
	global_store_dwordx2 v[14:15], v[12:13], off
	v_mov_b32_e32 v12, v49
	ds_bpermute_b32 v13, v40, v12
	s_cbranch_scc1 .LBB0_373
	v_mov_b32_e32 v14, v54
	v_mov_b32_e32 v15, v55
	s_waitcnt lgkmcnt(0)
	v_mul_f32_e32 v13, v15, v13
	v_cndmask_b32_e64 v13, v13, -v13, s[10:11]
	v_fmac_f32_e32 v13, v12, v14
	v_mov_b32_e32 v12, v13
	s_branch .LBB0_373
